# v12: v10 + HGRN output S_prev staging loads batched + query-row loads in one round trip (no far-field exp split)
# speedup vs baseline: 1.0303x; 1.0023x over previous
.LBB0_1312:
	s_mov_b64 s[22:23], s[4:5]
	s_mov_b64 s[18:19], s[64:65]
	s_mov_b64 s[20:21], s[2:3]
	s_mov_b64 s[28:29], s[6:7]
	s_mov_b64 s[24:25], s[8:9]
	s_mov_b64 s[30:31], s[0:1]
	s_ashr_i32 s26, s54, 9
	v_lshl_add_u64 v[2:3], s[28:29], 0, v[34:35]
	v_lshl_add_u64 v[2:3], v[2:3], 0, s[14:15]
	flat_load_dwordx4 v[16:19], v[2:3]
	v_readfirstlane_b32 s12, v52
	s_ashr_i32 s27, s26, 31
	s_ashr_i32 s55, s12, 3
	s_and_b32 s57, s38, 0xfc0
	s_lshl_b64 s[26:27], s[26:27], 12
	s_andn2_b32 s55, s55, 31
	v_lshl_add_u64 v[4:5], s[28:29], 0, v[32:33]
	v_lshl_add_u64 v[6:7], s[28:29], 0, v[30:31]
	v_lshl_add_u64 v[8:9], s[28:29], 0, v[28:29]
	s_or_b32 s26, s26, s57
	s_ashr_i32 s29, s55, 31
	v_mov_b64_e32 v[0:1], s[30:31]
	v_lshl_add_u64 v[46:47], v[4:5], 0, s[14:15]
	s_add_u32 s28, s26, s55
	v_lshl_add_u64 v[4:5], s[26:27], 0, v[26:27]
	s_addc_u32 s29, s27, s29
	v_mad_u64_u32 v[0:1], s[26:27], v4, s36, v[0:1]
	v_lshl_add_u64 v[44:45], v[6:7], 0, s[14:15]
	v_or_b32_e32 v6, s55, v54
	s_lshl_b64 s[26:27], s[28:29], 12
	v_lshl_add_u64 v[42:43], v[8:9], 0, s[14:15]
	v_mul_lo_u32 v8, v6, s37
	v_lshlrev_b64 v[6:7], 11, v[4:5]
	s_add_u32 s22, s22, s26
	v_or_b32_e32 v2, s28, v20
	v_mov_b32_e32 v3, s29
	v_mad_i32_i24 v1, v5, s36, v1
	v_lshl_add_u64 v[4:5], s[24:25], 0, v[6:7]
	s_addc_u32 s23, s23, s27
	s_and_b32 s24, s10, 0x380
	v_lshlrev_b64 v[2:3], 11, v[2:3]
	s_lshl_b32 s25, s24, 2
	v_lshl_add_u64 v[2:3], s[20:21], 0, v[2:3]
	s_add_u32 s20, s22, s25
	s_addc_u32 s21, s23, 0
	s_lshr_b32 s12, s12, 1
	s_and_b32 s12, s12, 0x60
	s_lshl_b32 s22, s12, 2
	s_add_u32 s20, s20, s22
	s_addc_u32 s21, s21, 0
	v_lshl_add_u32 v65, s12, 1, v53
	s_lshl_b32 s12, s24, 1
	v_lshl_add_u64 v[6:7], s[20:21], 0, v[36:37]
	v_lshl_add_u64 v[4:5], v[4:5], 0, s[12:13]
	v_lshl_add_u64 v[6:7], v[6:7], 0, v[24:25]
	v_lshl_add_u64 v[48:49], v[4:5], 0, v[40:41]
	v_add_co_u32_e32 v4, vcc, s33, v6
	v_add3_u32 v131, v55, s22, v8
	s_nop 0
	v_addc_co_u32_e32 v5, vcc, 0, v7, vcc
	v_add_co_u32_e32 v8, vcc, s34, v6
	v_lshl_add_u64 v[2:3], v[2:3], 0, s[12:13]
	s_nop 0
	v_addc_co_u32_e32 v9, vcc, 0, v7, vcc
	v_add_co_u32_e32 v10, vcc, s35, v6
	v_lshl_add_u64 v[0:1], v[0:1], 0, s[12:13]
	s_nop 0
	v_addc_co_u32_e32 v11, vcc, 0, v7, vcc
	v_add_co_u32_e32 v12, vcc, s41, v6
	s_add_u32 s18, s18, s25
	s_nop 0
	v_addc_co_u32_e32 v13, vcc, 0, v7, vcc
	v_add_co_u32_e32 v14, vcc, s42, v6
	v_lshl_add_u64 v[2:3], v[2:3], 0, v[38:39]
	s_nop 0
	v_addc_co_u32_e32 v15, vcc, 0, v7, vcc
	v_add_co_u32_e32 v106, vcc, s43, v6
	v_lshl_add_u64 v[0:1], v[0:1], 0, v[40:41]
	s_nop 0
	v_addc_co_u32_e32 v107, vcc, 0, v7, vcc
	v_add_co_u32_e32 v108, vcc, s44, v6
	s_addc_u32 s19, s19, 0
	s_nop 0
	v_addc_co_u32_e32 v109, vcc, 0, v7, vcc
	v_add_co_u32_e32 v110, vcc, s45, v6
	flat_load_dwordx4 v[66:69], v[2:3]
	flat_load_dwordx4 v[70:73], v[2:3] offset:32
	flat_load_dwordx4 v[74:77], v[2:3] offset:64
	flat_load_dwordx4 v[78:81], v[2:3] offset:96
	flat_load_dwordx4 v[82:85], v[2:3] offset:128
	flat_load_dwordx4 v[86:89], v[2:3] offset:160
	flat_load_dwordx4 v[90:93], v[2:3] offset:192
	flat_load_dwordx4 v[94:97], v[2:3] offset:224
	flat_load_dwordx4 v[98:101], v[0:1]
	flat_load_dwordx4 v[102:105], v[0:1] offset:16
	v_addc_co_u32_e32 v111, vcc, 0, v7, vcc
	v_add_co_u32_e32 v112, vcc, s46, v6
	v_lshl_add_u64 v[126:127], s[18:19], 0, v[22:23]
	s_nop 0
	v_addc_co_u32_e32 v113, vcc, 0, v7, vcc
	v_add_co_u32_e32 v114, vcc, s47, v6
	v_add_u32_e32 v130, 0xa000, v65
	s_nop 0
	v_addc_co_u32_e32 v115, vcc, 0, v7, vcc
	v_add_co_u32_e32 v116, vcc, s48, v6
	v_add_u32_e32 v132, 0x400, v131
	s_nop 0
	v_addc_co_u32_e32 v117, vcc, 0, v7, vcc
	v_add_co_u32_e32 v118, vcc, s49, v6
	v_add_u32_e32 v133, 0x1000, v131
	s_nop 0
	v_addc_co_u32_e32 v119, vcc, 0, v7, vcc
	v_add_co_u32_e32 v120, vcc, s50, v6
	v_add_u32_e32 v134, 0x1400, v131
	s_nop 0
	v_addc_co_u32_e32 v121, vcc, 0, v7, vcc
	v_add_co_u32_e32 v122, vcc, s51, v6
	v_add_u32_e32 v135, 0x2000, v131
	s_nop 0
	v_addc_co_u32_e32 v123, vcc, 0, v7, vcc
	v_add_co_u32_e32 v124, vcc, s52, v6
	v_add_u32_e32 v136, 0x2400, v131
	s_nop 0
	v_addc_co_u32_e32 v125, vcc, 0, v7, vcc
	flat_load_dword v0, v[6:7]
	flat_load_dword v1, v[4:5]
	flat_load_dword v2, v[8:9]
	flat_load_dword v3, v[10:11]
	s_nop 0
	flat_load_dword v4, v[12:13]
	flat_load_dword v5, v[14:15]
	flat_load_dword v6, v[106:107]
	flat_load_dword v7, v[108:109]
	flat_load_dword v8, v[110:111]
	flat_load_dword v9, v[112:113]
	flat_load_dword v10, v[114:115]
	flat_load_dword v11, v[116:117]
	flat_load_dword v12, v[118:119]
	flat_load_dword v13, v[120:121]
	flat_load_dword v14, v[122:123]
	flat_load_dword v15, v[124:125]
	flat_load_dwordx4 v[106:109], v[126:127]
	flat_load_dwordx4 v[110:113], v[126:127] offset:16
	flat_load_dwordx4 v[114:117], v[126:127] offset:32
	flat_load_dwordx4 v[118:121], v[126:127] offset:48
	flat_load_dwordx4 v[240:243], v[46:47]
	flat_load_dwordx4 v[244:247], v[44:45]
	flat_load_dwordx4 v[248:251], v[42:43]
	s_waitcnt vmcnt(0) lgkmcnt(0)
	ds_write_b128 v60, v[16:19] offset:40960
	ds_write_b128 v61, v[240:243] offset:40960
	ds_write_b128 v62, v[244:247] offset:40960
	ds_write_b128 v63, v[248:251] offset:40960
	v_add_u32_e32 v137, 0x3000, v131
	v_add_u32_e32 v138, 0x3400, v131
	s_add_i32 s54, s54, s92
	s_add_i32 s38, s38, s39
	s_add_i32 s10, s10, s40
	s_add_u32 s14, s14, s16
	s_addc_u32 s15, s15, s17
	s_cmpk_gt_i32 s54, 0x3ff
	v_and_b32_e32 v125, 0xffff0000, v101
	v_and_b32_e32 v47, 0xffff0000, v104
	v_lshlrev_b32_e32 v46, 16, v104
	v_and_b32_e32 v129, 0xffff0000, v105
	v_lshlrev_b32_e32 v128, 16, v105
	v_lshlrev_b32_e32 v124, 16, v101
	v_and_b32_e32 v101, 0xffff0000, v100
	v_lshlrev_b32_e32 v100, 16, v100
	v_and_b32_e32 v127, 0xffff0000, v99
	v_lshlrev_b32_e32 v126, 16, v99
	v_and_b32_e32 v99, 0xffff0000, v98
	v_lshlrev_b32_e32 v98, 16, v98
	v_and_b32_e32 v123, 0xffff0000, v103
	v_lshlrev_b32_e32 v122, 16, v103
	v_and_b32_e32 v103, 0xffff0000, v102
	v_lshlrev_b32_e32 v102, 16, v102
	s_waitcnt vmcnt(0) lgkmcnt(0)
	s_barrier
	ds_read_u16 v16, v65 offset:40960
	ds_read_u16 v17, v65 offset:41232
	ds_read_u16 v18, v65 offset:41504
	ds_read_u16 v19, v65 offset:41776
	ds_read_u16 v42, v65 offset:42048
	ds_read_u16 v43, v65 offset:42320
	ds_read_u16 v44, v65 offset:42592
	ds_read_u16 v45, v65 offset:42864
	ds_read_u16 v104, v65 offset:45312
	ds_read_u16 v105, v65 offset:45584
	ds_read_u16 v139, v65 offset:45856
	ds_read_u16 v140, v65 offset:46128
	ds_read_u16 v141, v65 offset:46400
	ds_read_u16 v142, v65 offset:46672
	ds_read_u16 v143, v65 offset:46944
	ds_read_u16 v144, v65 offset:47216
	ds_read_u16 v145, v65 offset:49664
	ds_read_u16 v146, v65 offset:49936
	ds_read_u16 v147, v65 offset:50208
	ds_read_u16 v148, v65 offset:50480
	ds_read_u16 v149, v65 offset:50752
	ds_read_u16 v150, v65 offset:51024
	ds_read_u16 v151, v65 offset:51296
	ds_read_u16 v152, v65 offset:51568
	ds_read_u16 v153, v65 offset:54016
	ds_read_u16 v154, v65 offset:54288
	ds_read_u16 v155, v65 offset:54560
	ds_read_u16 v156, v65 offset:54832
	ds_read_u16 v157, v65 offset:55104
	ds_read_u16 v158, v65 offset:55376
	ds_read_u16 v159, v65 offset:55648
	ds_read_u16 v160, v65 offset:55920
	ds_read_u16 v161, v65 offset:58368
	ds_read_u16 v162, v65 offset:58640
	ds_read_u16 v163, v65 offset:58912
	ds_read_u16 v164, v65 offset:59184
	ds_read_u16 v165, v65 offset:59456
	ds_read_u16 v166, v65 offset:59728
	ds_read_u16 v167, v65 offset:60000
	ds_read_u16 v168, v65 offset:60272
	ds_read_u16 v169, v65 offset:62720
	ds_read_u16 v170, v65 offset:62992
	ds_read_u16 v171, v65 offset:63264
	ds_read_u16 v172, v65 offset:63536
	s_waitcnt lgkmcnt(14)
	v_lshl_or_b32 v16, v17, 16, v16
	v_lshl_or_b32 v17, v19, 16, v18
	v_lshl_or_b32 v18, v43, 16, v42
	v_lshl_or_b32 v19, v45, 16, v44
	ds_read_u16 v42, v65 offset:63808
	ds_read_u16 v43, v65 offset:64080
	ds_read_u16 v44, v65 offset:64352
	v_mfma_f32_32x32x16_bf16 v[0:15], v[66:69], v[16:19], v[0:15]
	v_lshl_or_b32 v16, v105, 16, v104
	v_lshl_or_b32 v17, v140, 16, v139
	v_lshl_or_b32 v18, v142, 16, v141
	v_lshl_or_b32 v19, v144, 16, v143
	ds_read_u16 v45, v65 offset:64624
	ds_read_u16 v65, v130 offset:26112
	ds_read_u16 v66, v130 offset:26384
	ds_read_u16 v67, v130 offset:26656
	ds_read_u16 v68, v130 offset:26928
	ds_read_u16 v69, v130 offset:27200
	v_mfma_f32_32x32x16_bf16 v[0:15], v[70:73], v[16:19], v[0:15]
	v_lshl_or_b32 v16, v146, 16, v145
	v_lshl_or_b32 v17, v148, 16, v147
	v_lshl_or_b32 v18, v150, 16, v149
	v_lshl_or_b32 v19, v152, 16, v151
	ds_read_u16 v70, v130 offset:27472
	ds_read_u16 v71, v130 offset:27744
	ds_read_u16 v72, v130 offset:28016
	v_mfma_f32_32x32x16_bf16 v[0:15], v[74:77], v[16:19], v[0:15]
	v_lshl_or_b32 v16, v154, 16, v153
	v_lshl_or_b32 v17, v156, 16, v155
	v_lshl_or_b32 v18, v158, 16, v157
	s_waitcnt lgkmcnt(14)
	v_lshl_or_b32 v19, v160, 16, v159
	ds_read_u16 v73, v130 offset:30464
	ds_read_u16 v74, v130 offset:30736
	ds_read_u16 v75, v130 offset:31008
	v_mfma_f32_32x32x16_bf16 v[0:15], v[78:81], v[16:19], v[0:15]
	v_lshl_or_b32 v16, v162, 16, v161
	v_lshl_or_b32 v17, v164, 16, v163
	v_lshl_or_b32 v18, v166, 16, v165
	v_lshl_or_b32 v19, v168, 16, v167
	s_nop 1
	v_mfma_f32_32x32x16_bf16 v[0:15], v[82:85], v[16:19], v[0:15]
	v_lshl_or_b32 v16, v170, 16, v169
	s_waitcnt lgkmcnt(14)
	v_lshl_or_b32 v17, v172, 16, v171
	s_waitcnt lgkmcnt(13)
	v_lshl_or_b32 v18, v43, 16, v42
	s_waitcnt lgkmcnt(11)
	v_lshl_or_b32 v19, v45, 16, v44
	ds_read_u16 v42, v130 offset:31280
	ds_read_u16 v43, v130 offset:31552
	ds_read_u16 v44, v130 offset:31824
	v_mfma_f32_32x32x16_bf16 v[0:15], v[86:89], v[16:19], v[0:15]
	s_waitcnt lgkmcnt(12)
	v_lshl_or_b32 v16, v66, 16, v65
	s_waitcnt lgkmcnt(10)
	v_lshl_or_b32 v17, v68, 16, v67
	s_waitcnt lgkmcnt(8)
	v_lshl_or_b32 v18, v70, 16, v69
	s_waitcnt lgkmcnt(6)
	v_lshl_or_b32 v19, v72, 16, v71
	s_nop 1
	v_mfma_f32_32x32x16_bf16 v[0:15], v[90:93], v[16:19], v[0:15]
	ds_read_u16 v19, v130 offset:32096
	ds_read_u16 v45, v130 offset:32368
	s_waitcnt lgkmcnt(6)
	v_lshl_or_b32 v16, v74, 16, v73
	s_waitcnt lgkmcnt(4)
	v_lshl_or_b32 v17, v42, 16, v75
	s_waitcnt lgkmcnt(2)
	v_lshl_or_b32 v18, v44, 16, v43
	s_waitcnt lgkmcnt(0)
	v_lshl_or_b32 v19, v45, 16, v19
	s_nop 1
	v_mfma_f32_32x32x16_bf16 v[0:15], v[94:97], v[16:19], v[0:15]
	s_nop 11
	ds_write2_b32 v131, v0, v1 offset1:132
	ds_write2_b32 v132, v2, v3 offset0:8 offset1:140
	ds_write2_b32 v133, v4, v5 offset0:32 offset1:164
	ds_write2_b32 v134, v6, v7 offset0:40 offset1:172
	ds_write2_b32 v135, v8, v9 offset0:64 offset1:196
	ds_write2_b32 v136, v10, v11 offset0:72 offset1:204
	ds_write2_b32 v137, v12, v13 offset0:96 offset1:228
	ds_write2_b32 v138, v14, v15 offset0:104 offset1:236
	s_waitcnt lgkmcnt(0)
	s_barrier
	ds_read_b128 v[0:3], v56 offset:48
	ds_read_b128 v[4:7], v56 offset:32
	ds_read_b128 v[8:11], v56
	ds_read_b128 v[12:15], v56 offset:16
	s_waitcnt lgkmcnt(3)
	v_pk_mul_f32 v[18:19], v[0:1], v[0:1]
	s_waitcnt lgkmcnt(2)
	v_pk_mul_f32 v[44:45], v[4:5], v[4:5]
	s_waitcnt lgkmcnt(1)
	v_pk_mul_f32 v[72:73], v[8:9], v[8:9]
	v_pk_mul_f32 v[70:71], v[10:11], v[10:11]
	v_add_f32_e32 v65, v72, v73
	v_add_f32_e32 v65, v65, v70
	s_waitcnt lgkmcnt(0)
	v_pk_mul_f32 v[68:69], v[12:13], v[12:13]
	v_add_f32_e32 v65, v65, v71
	v_add_f32_e32 v65, v65, v68
	v_pk_mul_f32 v[66:67], v[14:15], v[14:15]
	v_add_f32_e32 v65, v65, v69
	v_add_f32_e32 v65, v65, v66
	v_add_f32_e32 v65, v65, v67
	v_add_f32_e32 v44, v65, v44
	v_pk_mul_f32 v[42:43], v[6:7], v[6:7]
	v_add_f32_e32 v44, v44, v45
	v_add_f32_e32 v42, v44, v42
	v_add_f32_e32 v42, v42, v43
	v_add_f32_e32 v18, v42, v18
	v_pk_mul_f32 v[16:17], v[2:3], v[2:3]
	v_add_f32_e32 v18, v18, v19
	v_add_f32_e32 v16, v18, v16
	v_add_f32_e32 v16, v16, v17
	ds_bpermute_b32 v17, v57, v16
	s_waitcnt lgkmcnt(0)
	v_add_f32_e32 v16, v16, v17
	ds_bpermute_b32 v17, v58, v16
	s_waitcnt lgkmcnt(0)
	v_add_f32_e32 v16, v16, v17
	ds_bpermute_b32 v17, v59, v16
	s_waitcnt lgkmcnt(0)
	v_add_f32_e32 v16, v16, v17
	v_fmamk_f32 v16, v16, 0x3c000000, v64
	v_mul_f32_e32 v17, 0x4b800000, v16
	v_cmp_gt_f32_e32 vcc, s53, v16
	s_nop 1
	v_cndmask_b32_e32 v16, v16, v17, vcc
	v_rsq_f32_e32 v16, v16
	s_nop 0
	v_mul_f32_e32 v17, 0x45800000, v16
	v_cndmask_b32_e32 v16, v16, v17, vcc
	v_pk_mul_f32 v[8:9], v[8:9], v[16:17] op_sel_hi:[1,0]
	v_pk_mul_f32 v[10:11], v[10:11], v[16:17] op_sel_hi:[1,0]
	v_pk_mul_f32 v[12:13], v[12:13], v[16:17] op_sel_hi:[1,0]
	v_pk_mul_f32 v[14:15], v[14:15], v[16:17] op_sel_hi:[1,0]
	v_pk_mul_f32 v[4:5], v[4:5], v[16:17] op_sel_hi:[1,0]
	v_pk_mul_f32 v[6:7], v[6:7], v[16:17] op_sel_hi:[1,0]
	v_pk_mul_f32 v[0:1], v[0:1], v[16:17] op_sel_hi:[1,0]
	v_pk_mul_f32 v[2:3], v[2:3], v[16:17] op_sel_hi:[1,0]
	v_pk_mul_f32 v[8:9], v[106:107], v[8:9]
	v_pk_mul_f32 v[10:11], v[108:109], v[10:11]
	v_pk_mul_f32 v[12:13], v[110:111], v[12:13]
	v_pk_mul_f32 v[14:15], v[112:113], v[14:15]
	v_pk_mul_f32 v[4:5], v[114:115], v[4:5]
	v_pk_mul_f32 v[6:7], v[116:117], v[6:7]
	v_pk_mul_f32 v[0:1], v[118:119], v[0:1]
	v_pk_mul_f32 v[2:3], v[120:121], v[2:3]
	v_pk_mul_f32 v[8:9], v[8:9], v[98:99]
	v_pk_mul_f32 v[10:11], v[10:11], v[126:127]
	v_pk_mul_f32 v[12:13], v[12:13], v[100:101]
	v_pk_mul_f32 v[14:15], v[14:15], v[124:125]
	v_pk_mul_f32 v[4:5], v[4:5], v[102:103]
	v_pk_mul_f32 v[6:7], v[6:7], v[122:123]
	v_pk_mul_f32 v[16:17], v[0:1], v[46:47]
	v_pk_mul_f32 v[18:19], v[2:3], v[128:129]
	v_cvt_pk_bf16_f32 v0, v8, v9
	v_cvt_pk_bf16_f32 v1, v10, v11
	v_cvt_pk_bf16_f32 v2, v12, v13
	v_cvt_pk_bf16_f32 v3, v14, v15
	v_cvt_pk_bf16_f32 v4, v4, v5
	v_cvt_pk_bf16_f32 v5, v6, v7
	v_cvt_pk_bf16_f32 v6, v16, v17
	v_cvt_pk_bf16_f32 v7, v18, v19
	flat_store_dwordx4 v[48:49], v[0:3]
	flat_store_dwordx4 v[48:49], v[4:7] offset:16
	s_waitcnt lgkmcnt(0)
	s_barrier
	s_cbranch_scc0 .LBB0_1312
	v_mov_b32_e32 v217, s11

.LBB0_1339:
	s_or_b64 exec, exec, s[44:45]
	s_lshl_b32 s44, s36, 5
	s_xor_b64 s[80:81], s[6:7], -1
	s_or_b32 s6, s44, s59
	v_bfe_u32 v147, v224, 2, 3
	v_or_b32_e32 v130, s6, v147
	v_and_b32_e32 v132, 3, v224
	v_ashrrev_i32_e32 v131, 31, v130
	v_or_b32_e32 v8, s66, v132
	v_lshl_add_u64 v[2:3], s[34:35], 0, v[130:131]
	v_mov_b64_e32 v[4:5], s[8:9]
	s_movk_i32 s8, 0x60
	v_mul_u32_u24_e32 v6, 3, v8
	v_mad_u64_u32 v[4:5], s[6:7], v2, s8, v[4:5]
	v_mad_i32_i24 v5, v3, s8, v5
	v_lshlrev_b32_e32 v6, 2, v6
	v_mov_b32_e32 v7, v0
	v_lshl_add_u64 v[4:5], v[4:5], 0, v[6:7]
	flat_load_dwordx3 v[208:210], v[4:5]
	v_mov_b64_e32 v[4:5], s[4:5]
	s_movk_i32 s6, 0x1100
	v_mad_u64_u32 v[4:5], s[4:5], v2, s6, v[4:5]
	v_ashrrev_i32_e32 v146, 5, v224
	v_mad_i32_i24 v5, v3, s6, v5
	v_lshlrev_b32_e32 v2, 9, v8
	v_mov_b32_e32 v3, v0
	v_lshl_add_u64 v[2:3], v[4:5], 0, v[2:3]
	v_lshlrev_b32_e32 v4, 3, v146
	v_ashrrev_i32_e32 v5, 31, v4
	v_lshlrev_b64 v[66:67], 2, v[4:5]
	v_lshl_add_u64 v[34:35], v[2:3], 0, v[66:67]
	flat_load_dwordx4 v[14:17], v[34:35]
	flat_load_dwordx4 v[10:13], v[34:35] offset:16
	flat_load_dwordx4 v[6:9], v[34:35] offset:64
	flat_load_dwordx4 v[2:5], v[34:35] offset:80
	flat_load_dwordx4 v[140:143], v[34:35] offset:128
	flat_load_dwordx4 v[148:151], v[34:35] offset:144
	flat_load_dwordx4 v[152:155], v[34:35] offset:192
	flat_load_dwordx4 v[156:159], v[34:35] offset:208
	flat_load_dwordx4 v[160:163], v[34:35] offset:256
	flat_load_dwordx4 v[164:167], v[34:35] offset:272
	flat_load_dwordx4 v[168:171], v[34:35] offset:320
	flat_load_dwordx4 v[172:175], v[34:35] offset:336
	flat_load_dwordx4 v[240:243], v[34:35] offset:384
	flat_load_dwordx4 v[244:247], v[34:35] offset:400
	flat_load_dwordx4 v[248:251], v[34:35] offset:448
	flat_load_dwordx4 v[252:255], v[34:35] offset:464
	v_lshl_add_u64 v[98:99], s[2:3], 0, v[66:67]
	v_mul_lo_u32 v1, v1, s65
	v_lshlrev_b32_e32 v133, 2, v133
	s_waitcnt vmcnt(0) lgkmcnt(0)
	v_mul_f32_e32 v137, 0x3fb8aa3b, v137
	v_add3_u32 v1, s63, v1, v133
	v_mov_b32_e32 v20, v15
	v_mov_b32_e32 v18, v14
	v_mov_b32_e32 v21, v7
	v_mov_b32_e32 v19, v6
	v_pk_mul_f32 v[20:21], v[20:21], v[20:21]
	v_mov_b32_e32 v22, v17
	v_mov_b32_e32 v23, v9
	v_pk_fma_f32 v[18:19], v[18:19], v[18:19], v[20:21]
	v_mov_b32_e32 v20, v16
	v_mov_b32_e32 v21, v8
	v_pk_mul_f32 v[22:23], v[22:23], v[22:23]
	s_nop 0
	v_pk_fma_f32 v[20:21], v[20:21], v[20:21], v[22:23]
	v_mov_b32_e32 v22, v11
	v_mov_b32_e32 v23, v3
	v_pk_add_f32 v[18:19], v[18:19], v[20:21]
	v_mov_b32_e32 v20, v10
	v_mov_b32_e32 v21, v2
	v_pk_mul_f32 v[22:23], v[22:23], v[22:23]
	s_nop 0
	v_pk_fma_f32 v[20:21], v[20:21], v[20:21], v[22:23]
	v_mov_b32_e32 v22, v13
	v_mov_b32_e32 v23, v5
	v_pk_add_f32 v[18:19], v[18:19], v[20:21]
	v_mov_b32_e32 v20, v12
	v_mov_b32_e32 v21, v4
	v_pk_mul_f32 v[22:23], v[22:23], v[22:23]
	s_nop 0
	v_pk_fma_f32 v[20:21], v[20:21], v[20:21], v[22:23]
	v_mov_b64_e32 v[30:31], v[140:141]
	v_mov_b64_e32 v[32:33], v[142:143]
	v_mov_b64_e32 v[22:23], v[148:149]
	v_mov_b64_e32 v[24:25], v[150:151]
	v_pk_add_f32 v[36:37], v[20:21], v[18:19]
	s_waitcnt vmcnt(0) lgkmcnt(0)
	v_pk_mul_f32 v[18:19], v[32:33], v[32:33]
	v_pk_mul_f32 v[20:21], v[30:31], v[30:31]
	v_pk_add_f32 v[36:37], v[36:37], v[36:37] op_sel:[0,1] op_sel_hi:[1,0]
	v_pk_mov_b32 v[26:27], v[20:21], v[18:19] op_sel:[1,0]
	v_mov_b32_e32 v21, v19
	v_pk_add_f32 v[18:19], v[26:27], v[20:21]
	v_pk_mul_f32 v[20:21], v[24:25], v[24:25]
	v_pk_mul_f32 v[26:27], v[22:23], v[22:23]
	v_mov_b32_e32 v28, v20
	v_mov_b32_e32 v29, v26
	v_mov_b32_e32 v26, v21
	v_pk_add_f32 v[18:19], v[18:19], v[18:19] op_sel:[0,1] op_sel_hi:[1,0]
	v_pk_add_f32 v[20:21], v[28:29], v[26:27]
	s_nop 0
	v_pk_add_f32 v[18:19], v[18:19], v[20:21] op_sel:[0,1] op_sel_hi:[1,0]
	s_nop 0
	v_pk_add_f32 v[38:39], v[20:21], v[18:19]
	v_mov_b64_e32 v[26:27], v[152:153]
	v_mov_b64_e32 v[28:29], v[154:155]
	v_mov_b64_e32 v[18:19], v[156:157]
	v_mov_b64_e32 v[20:21], v[158:159]
	v_mov_b64_e32 v[50:51], v[160:161]
	v_mov_b64_e32 v[52:53], v[162:163]
	v_mov_b64_e32 v[42:43], v[164:165]
	v_mov_b64_e32 v[44:45], v[166:167]
	s_waitcnt vmcnt(0) lgkmcnt(0)
	v_mov_b32_e32 v46, v19
	v_mov_b32_e32 v47, v51
	v_mov_b32_e32 v40, v18
	v_mov_b32_e32 v41, v50
	v_pk_mul_f32 v[46:47], v[46:47], v[46:47]
	v_mul_f32_e32 v48, v52, v52
	v_pk_fma_f32 v[40:41], v[40:41], v[40:41], v[46:47]
	v_mul_f32_e32 v46, v27, v27
	v_pk_fma_f32 v[46:47], v[26:27], v[26:27], v[46:47] op_sel_hi:[1,1,0]
	v_mul_f32_e32 v54, v53, v53
	v_mov_b32_e32 v47, v48
	v_mul_f32_e32 v48, v29, v29
	v_mul_f32_e32 v55, v44, v44
	v_pk_fma_f32 v[48:49], v[28:29], v[28:29], v[48:49] op_sel_hi:[1,1,0]
	v_mov_b32_e32 v37, v55
	v_mov_b32_e32 v49, v54
	v_mov_b64_e32 v[62:63], v[168:169]
	v_mov_b64_e32 v[64:65], v[170:171]
	v_mov_b64_e32 v[54:55], v[172:173]
	v_mov_b64_e32 v[56:57], v[174:175]
	v_pk_add_f32 v[46:47], v[46:47], v[48:49]
	v_mov_b32_e32 v48, v21
	v_mov_b32_e32 v49, v43
	v_pk_add_f32 v[40:41], v[40:41], v[46:47]
	v_mov_b32_e32 v46, v20
	v_mov_b32_e32 v47, v42
	v_pk_mul_f32 v[48:49], v[48:49], v[48:49]
	v_mul_f32_e32 v39, v45, v45
	v_pk_fma_f32 v[46:47], v[46:47], v[46:47], v[48:49]
	v_pk_add_f32 v[36:37], v[36:37], v[38:39]
	v_pk_add_f32 v[40:41], v[40:41], v[46:47]
	s_waitcnt vmcnt(0) lgkmcnt(0)
	v_pk_mul_f32 v[38:39], v[62:63], v[62:63]
	v_pk_add_f32 v[68:69], v[36:37], v[40:41]
	v_pk_mul_f32 v[36:37], v[64:65], v[64:65]
	v_pk_add_f32 v[68:69], v[68:69], v[68:69] op_sel:[0,1] op_sel_hi:[1,0]
	v_pk_mov_b32 v[40:41], v[38:39], v[36:37] op_sel:[1,0]
	v_mov_b32_e32 v39, v37
	v_pk_add_f32 v[36:37], v[40:41], v[38:39]
	v_pk_mul_f32 v[38:39], v[56:57], v[56:57]
	v_pk_mul_f32 v[40:41], v[54:55], v[54:55]
	v_mov_b32_e32 v46, v38
	v_mov_b32_e32 v47, v40
	v_mov_b32_e32 v40, v39
	v_pk_add_f32 v[36:37], v[36:37], v[36:37] op_sel:[0,1] op_sel_hi:[1,0]
	v_pk_add_f32 v[38:39], v[46:47], v[40:41]
	s_nop 0
	v_pk_add_f32 v[36:37], v[36:37], v[38:39] op_sel:[0,1] op_sel_hi:[1,0]
	s_nop 0
	v_pk_add_f32 v[70:71], v[38:39], v[36:37]
	v_mov_b64_e32 v[58:59], v[240:241]
	v_mov_b64_e32 v[60:61], v[242:243]
	v_mov_b64_e32 v[46:47], v[244:245]
	v_mov_b64_e32 v[48:49], v[246:247]
	v_mov_b64_e32 v[38:39], v[248:249]
	v_mov_b64_e32 v[40:41], v[250:251]
	s_nop 0
	v_mov_b64_e32 v[34:35], v[252:253]
	v_mov_b64_e32 v[36:37], v[254:255]
	s_waitcnt vmcnt(0) lgkmcnt(0)
	v_mov_b32_e32 v74, v47
	v_mov_b32_e32 v75, v39
	v_mov_b32_e32 v72, v46
	v_mov_b32_e32 v73, v38
	v_pk_mul_f32 v[74:75], v[74:75], v[74:75]
	v_mul_f32_e32 v76, v40, v40
	v_pk_fma_f32 v[72:73], v[72:73], v[72:73], v[74:75]
	v_mul_f32_e32 v74, v59, v59
	v_pk_fma_f32 v[74:75], v[58:59], v[58:59], v[74:75] op_sel_hi:[1,1,0]
	v_mul_f32_e32 v78, v41, v41
	v_mov_b32_e32 v75, v76
	v_mul_f32_e32 v76, v61, v61
	v_pk_fma_f32 v[76:77], v[60:61], v[60:61], v[76:77] op_sel_hi:[1,1,0]
	v_mul_f32_e32 v79, v36, v36
	v_mov_b32_e32 v77, v78
	v_pk_add_f32 v[74:75], v[74:75], v[76:77]
	v_mov_b32_e32 v76, v49
	v_mov_b32_e32 v77, v35
	v_pk_add_f32 v[72:73], v[72:73], v[74:75]
	v_mov_b32_e32 v74, v48
	v_mov_b32_e32 v75, v34
	v_pk_mul_f32 v[76:77], v[76:77], v[76:77]
	v_mul_f32_e32 v71, v37, v37
	v_pk_fma_f32 v[74:75], v[74:75], v[74:75], v[76:77]
	v_mov_b32_e32 v69, v79
	v_pk_add_f32 v[72:73], v[72:73], v[74:75]
	v_pk_add_f32 v[68:69], v[68:69], v[70:71]
	s_nop 0
	v_pk_add_f32 v[68:69], v[68:69], v[72:73]
	s_nop 0
	v_add_f32_e32 v131, v68, v69
	flat_load_dwordx4 v[94:97], v[98:99]
	flat_load_dwordx4 v[90:93], v[98:99] offset:16
	flat_load_dwordx4 v[86:89], v[98:99] offset:64
	flat_load_dwordx4 v[82:85], v[98:99] offset:80
	flat_load_dwordx4 v[78:81], v[98:99] offset:128
	flat_load_dwordx4 v[74:77], v[98:99] offset:144
	flat_load_dwordx4 v[70:73], v[98:99] offset:192
	flat_load_dwordx4 v[66:69], v[98:99] offset:208
	flat_load_dwordx4 v[126:129], v[98:99] offset:256
	flat_load_dwordx4 v[122:125], v[98:99] offset:272
	flat_load_dwordx4 v[118:121], v[98:99] offset:320
	flat_load_dwordx4 v[114:117], v[98:99] offset:336
	flat_load_dwordx4 v[110:113], v[98:99] offset:384
	flat_load_dwordx4 v[106:109], v[98:99] offset:400
	flat_load_dwordx4 v[102:105], v[98:99] offset:448
	s_nop 0
	flat_load_dwordx4 v[98:101], v[98:99] offset:464
	ds_bpermute_b32 v139, v218, v131
	ds_write_b32 v1, v137
	s_and_saveexec_b64 s[2:3], s[0:1]
	s_cbranch_execz .LBB0_1341
	v_add_u32_e32 v1, v136, v135
	v_lshl_add_u32 v133, v1, 7, v1
	v_sub_u32_e32 v133, v134, v133
	v_mul_lo_u32 v1, v1, s65
	v_lshlrev_b32_e32 v133, 2, v133
	v_add3_u32 v1, s63, v1, v133
	ds_write_b32 v1, v138
